# FFN weight conversion moved ahead of LayerNorm1 inside their shared phase (LN1's bf16 output is then the most recent data when the up-projection GEMM starts)
# baseline (speedup 1.0000x reference)
; #define LAS __attribute__((address_space(3)))
; __device__ __forceinline__ int obid() { int b = blockIdx.x; asm volatile("" : "+s"(b)); return b; }
; __device__ __forceinline__ int ogrid() { int g = gridDim.x; asm volatile("" : "+s"(g)); return g; }
; #define PH(b) for (int rep_ = 0, nrep_ = (int)(((PH_MASK >> (b)) & 1) + ((REP_MASK >> (b)) & 1)); rep_ < nrep_; ++rep_)
; __device__ __forceinline__ void cvt_ffn(KP p, int l, LAS unsigned char* lds, int wv0) {
;   unsigned char* W = p->ws; const int f = obid(), st = ogrid();
;   cvt_job(lds, p->w_up + (size_t)l * DM * NUP, (bf16_t*)(W + O_WUP), nullptr, DM, NUP, NUP, 4, wv0, f, st);
; __global__ void __launch_bounds__(512, 2) mega(Params p_unused) {
;     ...
;     PH(12) ln_phase(xa, xa, xb, p->ln1_g + l * DM, p->ln1_b + l * DM, wv0);
;     PH(13) cvt_ffn(p, l, lds, wv0);
.LBB0_1158:
	s_or_b64 exec, exec, s[2:3]
	s_waitcnt lgkmcnt(0)
	s_barrier
	s_lshl_b32 s1, s53, 6
	s_load_dwordx2 s[4:5], s[54:55], 0xd0
	s_waitcnt lgkmcnt(0)
	s_load_dwordx2 s[6:7], s[54:55], 0x98
	s_mul_i32 s2, s66, 0x5800000
	s_mul_hi_u32 s3, s66, 0x5800000
	s_mov_b32 s8, s4
	s_mov_b32 s9, s5
	s_waitcnt lgkmcnt(0)
	s_add_u32 s6, s6, s2
	s_addc_u32 s7, s7, s3
	v_mbcnt_lo_u32_b32 v43, -1, 0
	v_mbcnt_hi_u32_b32 v43, -1, v43
	v_or_b32_e32 v43, s1, v43
	v_and_b32_e32 v44, 63, v43
	v_lshrrev_b32_e32 v40, 6, v43
	s_mov_b32 s10, 0xb000
	v_mul_lo_u32 v32, v40, s10
	v_lshl_add_u32 v32, v44, 2, v32
	v_add_u32_e32 v33, 0x58000, v32
	v_add_u32_e32 v34, 0xb0000, v32
	v_add_u32_e32 v35, 0x108000, v32
	v_add_u32_e32 v36, 0x160000, v32
	v_add_u32_e32 v37, 0x1b8000, v32
	v_add_u32_e32 v38, 0x210000, v32
	v_add_u32_e32 v39, 0x268000, v32
	v_mul_u32_u24_e32 v40, 65, v40
	v_add_lshl_u32 v40, v40, v44, 2
	v_and_b32_e32 v44, 7, v43
	v_lshlrev_b32_e32 v44, 3, v44
	v_lshrrev_b32_e32 v43, 3, v43
	v_mul_u32_u24_e32 v41, 65, v44
	v_add_lshl_u32 v41, v41, v43, 2
	s_movk_i32 s10, 0x800
	v_mul_lo_u32 v42, v43, s10
	v_add_lshl_u32 v42, v42, v44, 1
	s_mov_b32 s11, s82
	s_lshl_b32 s12, s60, 2
	s_mov_b32 s13, 0
	s_add_u32 s13, s13, s11
	s_and_b32 s18, s13, 31
	s_lshr_b32 s19, s13, 5
	s_lshl_b32 s18, s18, 6
	s_lshl_b32 s19, s19, 6
	s_and_b32 s20, s19, 0xff
	s_lshr_b32 s21, s19, 8
	s_lshl_b32 s21, s21, 7
	s_add_u32 s21, s21, s20
	s_add_u32 s22, s21, 0x1580
	s_cmp_lt_u32 s20, 0x80
	s_cselect_b32 s21, s21, s22
	s_mul_i32 s20, s18, 0xb000
	s_lshl_b32 s21, s21, 2
	s_add_u32 s20, s20, s21
	s_add_u32 s14, s6, s20
	s_addc_u32 s15, s7, 0
	s_cmp_lt_u32 s13, 0x1600
	s_cbranch_scc0 .Lcvtup_pl
	global_load_dword v0, v32, s[14:15] nt
	global_load_dword v1, v33, s[14:15] nt
	global_load_dword v2, v34, s[14:15] nt
	global_load_dword v3, v35, s[14:15] nt
	global_load_dword v4, v36, s[14:15] nt
	global_load_dword v5, v37, s[14:15] nt
	global_load_dword v6, v38, s[14:15] nt
	global_load_dword v7, v39, s[14:15] nt
	s_mul_i32 s13, s60, 1
	s_add_u32 s13, s13, s11
	s_and_b32 s18, s13, 31
	s_lshr_b32 s19, s13, 5
	s_lshl_b32 s18, s18, 6
	s_lshl_b32 s19, s19, 6
	s_and_b32 s20, s19, 0xff
	s_lshr_b32 s21, s19, 8
	s_lshl_b32 s21, s21, 7
	s_add_u32 s21, s21, s20
	s_add_u32 s22, s21, 0x1580
	s_cmp_lt_u32 s20, 0x80
	s_cselect_b32 s21, s21, s22
	s_mul_i32 s20, s18, 0xb000
	s_lshl_b32 s21, s21, 2
	s_add_u32 s20, s20, s21
	s_add_u32 s14, s6, s20
	s_addc_u32 s15, s7, 0
	s_cmp_lt_u32 s13, 0x1600
	s_cbranch_scc0 .Lcvtup_pl
	global_load_dword v8, v32, s[14:15] nt
	global_load_dword v9, v33, s[14:15] nt
	global_load_dword v10, v34, s[14:15] nt
	global_load_dword v11, v35, s[14:15] nt
	global_load_dword v12, v36, s[14:15] nt
	global_load_dword v13, v37, s[14:15] nt
	global_load_dword v14, v38, s[14:15] nt
	global_load_dword v15, v39, s[14:15] nt
	s_mul_i32 s13, s60, 2
	s_add_u32 s13, s13, s11
	s_and_b32 s18, s13, 31
	s_lshr_b32 s19, s13, 5
	s_lshl_b32 s18, s18, 6
	s_lshl_b32 s19, s19, 6
	s_and_b32 s20, s19, 0xff
	s_lshr_b32 s21, s19, 8
	s_lshl_b32 s21, s21, 7
	s_add_u32 s21, s21, s20
	s_add_u32 s22, s21, 0x1580
	s_cmp_lt_u32 s20, 0x80
	s_cselect_b32 s21, s21, s22
	s_mul_i32 s20, s18, 0xb000
	s_lshl_b32 s21, s21, 2
	s_add_u32 s20, s20, s21
	s_add_u32 s14, s6, s20
	s_addc_u32 s15, s7, 0
	s_cmp_lt_u32 s13, 0x1600
	s_cbranch_scc0 .Lcvtup_pl
	global_load_dword v16, v32, s[14:15] nt
	global_load_dword v17, v33, s[14:15] nt
	global_load_dword v18, v34, s[14:15] nt
	global_load_dword v19, v35, s[14:15] nt
	global_load_dword v20, v36, s[14:15] nt
	global_load_dword v21, v37, s[14:15] nt
	global_load_dword v22, v38, s[14:15] nt
	global_load_dword v23, v39, s[14:15] nt
	s_mul_i32 s13, s60, 3
	s_add_u32 s13, s13, s11
	s_and_b32 s18, s13, 31
	s_lshr_b32 s19, s13, 5
	s_lshl_b32 s18, s18, 6
	s_lshl_b32 s19, s19, 6
	s_and_b32 s20, s19, 0xff
	s_lshr_b32 s21, s19, 8
	s_lshl_b32 s21, s21, 7
	s_add_u32 s21, s21, s20
	s_add_u32 s22, s21, 0x1580
	s_cmp_lt_u32 s20, 0x80
	s_cselect_b32 s21, s21, s22
	s_mul_i32 s20, s18, 0xb000
	s_lshl_b32 s21, s21, 2
	s_add_u32 s20, s20, s21
	s_add_u32 s14, s6, s20
	s_addc_u32 s15, s7, 0
	s_cmp_lt_u32 s13, 0x1600
	s_cbranch_scc0 .Lcvtup_pl
	global_load_dword v24, v32, s[14:15] nt
	global_load_dword v25, v33, s[14:15] nt
	global_load_dword v26, v34, s[14:15] nt
	global_load_dword v27, v35, s[14:15] nt
	global_load_dword v28, v36, s[14:15] nt
	global_load_dword v29, v37, s[14:15] nt
	global_load_dword v30, v38, s[14:15] nt
	global_load_dword v31, v39, s[14:15] nt

; __device__ __forceinline__ int otid(int wv0) { int t = (wv0 << 6) | olane(); asm volatile("" : "+v"(t)); return t; }
; __device__ __forceinline__ int obid() { int b = blockIdx.x; asm volatile("" : "+s"(b)); return b; }
; __device__ __forceinline__ int ogrid() { int g = gridDim.x; asm volatile("" : "+s"(g)); return g; }
; __device__ __forceinline__ void ln_phase(const float* in, float* outf, bf16_t* outb, const float* g, const float* b, int wv0) {
;   const int tid_ = otid(wv0); const int lane = tid_ & 63, wv = obid() * 8 + (tid_ >> 6), nwv = ogrid() * 8;
;   f32x4 gg[8], bb[8];
; #pragma unroll
;   for (int i = 0; i < 8; ++i) { gg[i] = ((const f32x4*)g)[i * 64 + lane]; bb[i] = ((const f32x4*)b)[i * 64 + lane]; }
;   f32x4 vn[8];
;   if (wv < NTOK) { const f32x4* ir = (const f32x4*)(in + (size_t)wv * DM);
; #pragma unroll
;     for (int i = 0; i < 8; ++i) vn[i] = ir[i * 64 + lane]; }
;   for (int row = wv; row < NTOK; row += nwv) {
;     f32x4 v[8]; float s = 0.f;
; #pragma unroll
;     for (int i = 0; i < 8; ++i) v[i] = vn[i];
;     if (row + nwv < NTOK) { const f32x4* ir = (const f32x4*)(in + (size_t)(row + nwv) * DM);
; #pragma unroll
;       for (int i = 0; i < 8; ++i) vn[i] = ir[i * 64 + lane]; }
.Lcvtdn_end:
	s_waitcnt vmcnt(0)
	s_mov_b32 s0, -1
	s_load_dwordx2 s[4:5], s[54:55], 0xd0
	s_lshl_b32 s1, s53, 6
	v_mbcnt_lo_u32_b32 v0, s0, 0
	v_mbcnt_hi_u32_b32 v0, s0, v0
	v_or_b32_e32 v0, s1, v0
	s_mov_b32 s2, s82
	v_ashrrev_i32_e32 v1, 6, v0
	s_mov_b32 s0, s60
	v_lshl_add_u32 v130, s2, 3, v1
	v_cmp_gt_i32_e32 vcc, s61, v130
	s_and_saveexec_b64 s[6:7], vcc
	s_cbranch_execz .LBB0_1163
	s_load_dwordx4 s[8:11], s[54:55], 0x88
	s_lshl_b32 s2, s66, 11
	s_ashr_i32 s3, s2, 31
	s_lshl_b64 s[2:3], s[2:3], 2
	s_waitcnt vmcnt(8)
	v_and_b32_e32 v78, 63, v0
	s_waitcnt lgkmcnt(0)
	s_add_u32 s100, s4, 0x27700000
	s_addc_u32 s101, s5, 0
	s_add_u32 s8, s8, s2
	s_addc_u32 s9, s9, s3
	s_add_u32 s2, s10, s2
	v_lshlrev_b32_e32 v96, 4, v78
	s_addc_u32 s3, s11, s3
	global_load_dwordx4 v[0:3], v96, s[8:9]
	global_load_dwordx4 v[4:7], v96, s[8:9] offset:1024
	global_load_dwordx4 v[8:11], v96, s[2:3]
	global_load_dwordx4 v[12:15], v96, s[2:3] offset:1024
	global_load_dwordx4 v[16:19], v96, s[8:9] offset:2048
	global_load_dwordx4 v[20:23], v96, s[8:9] offset:3072
	global_load_dwordx4 v[24:27], v96, s[2:3] offset:2048
	global_load_dwordx4 v[28:31], v96, s[2:3] offset:3072
	v_ashrrev_i32_e32 v131, 31, v130
	v_lshlrev_b64 v[132:133], 13, v[130:131]
	v_lshl_add_u64 v[64:65], s[4:5], 0, v[132:133]
	s_mov_b64 s[10:11], 0x8900000
	v_or_b32_e32 v56, 0x1000, v96
	v_mov_b32_e32 v57, v97
	v_or_b32_e32 v58, 0x1400, v96
	v_mov_b32_e32 v59, v97
	v_or_b32_e32 v60, 0x1800, v96
	v_mov_b32_e32 v61, v97
	v_or_b32_e32 v62, 0x1c00, v96
	v_mov_b32_e32 v63, v97
	v_lshl_add_u64 v[64:65], v[64:65], 0, s[10:11]
	global_load_dwordx4 v[32:35], v56, s[8:9]
	global_load_dwordx4 v[36:39], v56, s[2:3]
	global_load_dwordx4 v[40:43], v58, s[8:9]
	global_load_dwordx4 v[44:47], v58, s[2:3]
	global_load_dwordx4 v[48:51], v60, s[8:9]
	global_load_dwordx4 v[52:55], v60, s[2:3]
	v_lshl_add_u64 v[76:77], v[64:65], 0, v[96:97]
	v_lshl_add_u64 v[56:57], v[64:65], 0, v[56:57]
	v_lshl_add_u64 v[58:59], v[64:65], 0, v[58:59]
	v_lshl_add_u64 v[60:61], v[64:65], 0, v[60:61]
	v_lshl_add_u64 v[64:65], v[64:65], 0, v[62:63]
	global_load_dwordx4 v[68:71], v[60:61], off
	s_nop 0
	global_load_dwordx4 v[64:67], v[64:65], off
	s_nop 0
	global_load_dwordx4 v[110:113], v[56:57], off
	global_load_dwordx4 v[72:75], v[58:59], off
	global_load_dwordx4 v[118:121], v[76:77], off offset:2048
	global_load_dwordx4 v[114:117], v[76:77], off offset:3072
	global_load_dwordx4 v[126:129], v[76:77], off
	global_load_dwordx4 v[122:125], v[76:77], off offset:1024
	s_nop 0
	global_load_dwordx4 v[56:59], v62, s[8:9]
	s_nop 0
	global_load_dwordx4 v[60:63], v62, s[2:3]
	v_and_b32_e32 v76, 64, v251
	v_add_u32_e32 v76, 64, v76
	v_xor_b32_e32 v77, 32, v251
	v_cmp_lt_i32_e32 vcc, v77, v76
	s_lshl_b32 s8, s0, 3
	v_lshlrev_b64 v[134:135], 12, v[130:131]
	v_cndmask_b32_e32 v77, v251, v77, vcc
	v_lshlrev_b32_e32 v138, 2, v77
	v_xor_b32_e32 v77, 16, v251
	v_cmp_lt_i32_e32 vcc, v77, v76
	v_lshl_or_b32 v134, v78, 3, v134
	s_ashr_i32 s9, s8, 31
	v_cndmask_b32_e32 v77, v251, v77, vcc
	v_lshlrev_b32_e32 v139, 2, v77
	v_xor_b32_e32 v77, 8, v251
	v_cmp_lt_i32_e32 vcc, v77, v76
	s_lshl_b64 s[10:11], s[8:9], 12
	v_or_b32_e32 v132, v132, v96
	v_cndmask_b32_e32 v77, v251, v77, vcc
	v_lshlrev_b32_e32 v140, 2, v77
	v_xor_b32_e32 v77, 4, v251
	v_cmp_lt_i32_e32 vcc, v77, v76
	s_lshl_b64 s[12:13], s[8:9], 13
	s_mov_b64 s[14:15], 0
	v_cndmask_b32_e32 v77, v251, v77, vcc
	v_lshlrev_b32_e32 v141, 2, v77
	v_xor_b32_e32 v77, 2, v251
	v_cmp_lt_i32_e32 vcc, v77, v76
	s_waitcnt vmcnt(9)
	v_mov_b64_e32 v[100:101], v[70:71]
	v_cndmask_b32_e32 v77, v251, v77, vcc
	v_lshlrev_b32_e32 v142, 2, v77
	v_xor_b32_e32 v77, 1, v251
	v_cmp_lt_i32_e32 vcc, v77, v76
	s_waitcnt vmcnt(8)
	v_mov_b64_e32 v[94:95], v[66:67]
	s_waitcnt vmcnt(6)
	v_mov_b64_e32 v[104:105], v[74:75]
	v_cndmask_b32_e32 v76, v251, v77, vcc
	v_lshlrev_b32_e32 v143, 2, v76
	v_add_u32_e32 v76, s8, v130
	v_ashrrev_i32_e32 v77, 31, v76
	v_lshlrev_b64 v[136:137], 13, v[76:77]
	v_mov_b64_e32 v[106:107], v[110:111]
	s_waitcnt vmcnt(4)
	v_mov_b64_e32 v[76:77], v[114:115]
	v_mov_b64_e32 v[80:81], v[118:119]
	s_waitcnt vmcnt(2)
	v_mov_b64_e32 v[84:85], v[122:123]
	v_mov_b64_e32 v[88:89], v[126:127]
	v_or_b32_e32 v136, v136, v96
	v_mov_b64_e32 v[92:93], v[64:65]
	v_mov_b64_e32 v[98:99], v[68:69]
	v_mov_b64_e32 v[102:103], v[72:73]
	v_mov_b64_e32 v[108:109], v[112:113]
	v_mov_b64_e32 v[78:79], v[116:117]
	v_mov_b64_e32 v[82:83], v[120:121]
	v_mov_b64_e32 v[86:87], v[124:125]
	v_mov_b64_e32 v[90:91], v[128:129]
	s_branch .LBB0_1161

; #define LAS __attribute__((address_space(3)))
; __device__ __forceinline__ int otid(int wv0) { int t = (wv0 << 6) | olane(); asm volatile("" : "+v"(t)); return t; }
; __device__ __forceinline__ unsigned xb_add(unsigned* p, unsigned v) { return __hip_atomic_fetch_add(p, v, __ATOMIC_RELAXED, __HIP_MEMORY_SCOPE_AGENT); }
; __device__ __forceinline__ unsigned xb_xcc_id() { return (unsigned)__builtin_amdgcn_s_getreg((3 << 11) | 20) & 0xFu; }
; __device__ __forceinline__ void xcd_barrier(unsigned* bar, volatile LAS unsigned* st, int wv0) {
;     asm volatile("s_waitcnt vmcnt(0)" ::: "memory");
;     __syncthreads();
;     if (otid(wv0) == 0) {
;         const unsigned x = xb_xcc_id();
;         __builtin_amdgcn_s_waitcnt(0);
;         unsigned nloc = st[0], nx = st[1];
;         if (nloc == 0u) { xcd_barrier_complete(bar, x, nloc, nx); st[0] = nloc; st[1] = nx; }
;         const unsigned old = xb_add(&bar[XB_XSUB(x)], 1u);
.LBB0_1163:
	s_or_b64 exec, exec, s[6:7]
.LBB0_1207:
	s_mov_b32 s0, -1
	s_waitcnt vmcnt(0)
	s_waitcnt lgkmcnt(0)
	s_barrier
	s_waitcnt vmcnt(1)
	v_mbcnt_lo_u32_b32 v0, s0, 0
	v_mbcnt_hi_u32_b32 v0, s0, v0
	v_or_b32_e32 v0, s1, v0
	s_nop 0
	v_cmp_eq_u32_e32 vcc, 0, v0
	s_and_saveexec_b64 s[0:1], vcc
	s_xor_b64 s[2:3], exec, s[0:1]
	s_cbranch_execz .LBB0_1260
	s_add_i32 s1, 0, 0x20000
	v_mov_b32_e32 v0, s1
	s_getreg_b32 s0, hwreg(HW_REG_XCC_ID, 0, 4)
	s_waitcnt vmcnt(0) expcnt(0) lgkmcnt(0)
	ds_read_b32 v2, v0
	v_mov_b32_e32 v0, s76
	ds_read_b32 v0, v0
	s_and_b32 s0, s0, 15
	s_waitcnt lgkmcnt(1)
	v_cmp_ne_u32_e32 vcc, 0, v2
	s_cbranch_vccnz .LBB0_1223
	s_add_u32 s6, s4, 0x27740200
	s_addc_u32 s7, s5, 0
	s_add_u32 s8, s4, 0x27740400
	s_addc_u32 s9, s5, 0
	s_add_u32 s10, s4, 0x27740500
	s_addc_u32 s11, s5, 0
	s_add_u32 s12, s4, 0x27740600
	s_addc_u32 s13, s5, 0
	s_add_u32 s14, s4, 0x27740700
	s_addc_u32 s15, s5, 0
	s_add_u32 s16, s4, 0x27740800
	s_addc_u32 s17, s5, 0
	s_add_u32 s18, s4, 0x27740900
	s_addc_u32 s19, s5, 0
	s_add_u32 s20, s4, 0x27740a00
	s_addc_u32 s21, s5, 0
	s_add_u32 s22, s4, 0x27740b00
	s_addc_u32 s23, s5, 0
	s_add_u32 s24, s4, 0x27740c00
	s_addc_u32 s25, s5, 0
	s_add_u32 s26, s4, 0x27740d00
	s_addc_u32 s27, s5, 0
	s_add_u32 s28, s4, 0x27740e00
	s_addc_u32 s29, s5, 0
	s_add_u32 s30, s4, 0x27740f00
	s_addc_u32 s31, s5, 0
	s_add_u32 s34, s4, 0x27741000
	s_addc_u32 s35, s5, 0
	s_add_u32 s36, s4, 0x27741100
	s_addc_u32 s37, s5, 0
	s_add_u32 s38, s4, 0x27741200
	s_addc_u32 s39, s5, 0
	s_add_u32 s40, s4, 0x27741300
	s_addc_u32 s41, s5, 0
	s_mov_b32 s48, 1
	s_branch .LBB0_1211
